# nsa_skip_ps_for_invalid_compressed_tiles
# speedup vs baseline: 1.0168x; 1.0036x over previous
.LBB0_477:
	s_or_b64 exec, exec, s[0:1]
	s_lshr_b32 s98, s14, 4
	s_add_i32 s98, s98, 64
	s_lshr_b32 s98, s98, 6
	s_cmp_le_u32 s98, 1
	s_cbranch_scc1 .Lnsa_ps_end
	v_mul_f32_e32 v47, v65, v11
	s_nop 1
	v_mov_b32_dpp v49, v47 quad_perm:[1,0,3,2] row_mask:0xf bank_mask:0xf
	v_fmac_f32_e32 v49, v65, v11
	s_nop 1
	v_mov_b32_dpp v50, v49 quad_perm:[2,3,0,1] row_mask:0xf bank_mask:0xf
	s_and_saveexec_b64 s[0:1], vcc
	s_cbranch_execz .LBB0_479
	v_add_f32_e32 v49, v49, v50
	ds_write_b32 v15, v49 offset:256

.LBB0_509:
	s_or_b64 exec, exec, s[0:1]
	s_lshr_b32 s98, s14, 4
	s_add_i32 s98, s98, 64
	s_lshr_b32 s98, s98, 6
	s_cmp_le_u32 s98, 2
	s_cbranch_scc1 .Lnsa_ps_end
	v_mul_f32_e32 v66, v64, v11
	s_nop 1
	v_mov_b32_dpp v123, v66 quad_perm:[1,0,3,2] row_mask:0xf bank_mask:0xf
	v_fmac_f32_e32 v123, v64, v11
	s_nop 1
	v_mov_b32_dpp v64, v123 quad_perm:[2,3,0,1] row_mask:0xf bank_mask:0xf
	s_and_saveexec_b64 s[0:1], vcc
	s_cbranch_execz .LBB0_511
	v_add_f32_e32 v64, v123, v64
	ds_write_b32 v15, v64 offset:512

.LBB0_541:
	s_or_b64 exec, exec, s[0:1]
	s_lshr_b32 s98, s14, 4
	s_add_i32 s98, s98, 64
	s_lshr_b32 s98, s98, 6
	s_cmp_le_u32 s98, 3
	s_cbranch_scc1 .Lnsa_ps_end
	v_mul_f32_e32 v40, v38, v11
	s_nop 1
	v_mov_b32_dpp v39, v40 quad_perm:[1,0,3,2] row_mask:0xf bank_mask:0xf
	v_fmac_f32_e32 v39, v38, v11
	s_nop 1
	v_mov_b32_dpp v38, v39 quad_perm:[2,3,0,1] row_mask:0xf bank_mask:0xf
	s_and_saveexec_b64 s[0:1], vcc
	s_cbranch_execz .LBB0_543
	v_add_f32_e32 v38, v39, v38
	ds_write_b32 v15, v38 offset:768

.Lnsa_ps_end:
	v_and_b32_e32 v38, 15, v75
	v_lshl_add_u32 v115, v115, 1, 0
	s_movk_i32 s0, 0x210
	v_or_b32_e32 v39, 48, v113
	v_cvt_pk_bf16_f32 v16, v10, v16
	s_waitcnt lgkmcnt(0)
	v_mad_u32_u24 v8, v38, s0, v115
	v_mad_u32_u24 v10, v39, s0, v115
	v_cvt_pk_bf16_f32 v17, v18, v23
	v_cvt_pk_bf16_f32 v18, v25, v28
	v_cvt_pk_bf16_f32 v19, v31, v33
	ds_read_b128 v[20:23], v8 offset:38912
	ds_read_b128 v[24:27], v8 offset:47360
	ds_read_b128 v[28:31], v8 offset:55808
	ds_read_b128 v[136:139], v10 offset:38912
	s_waitcnt lgkmcnt(3)
	v_mfma_f32_16x16x32_bf16 v[20:23], v[20:23], v[16:19], 0
	v_cvt_pk_bf16_f32 v32, v32, v34
	v_cvt_pk_bf16_f32 v33, v35, v42
	v_cvt_pk_bf16_f32 v34, v44, v45
	s_waitcnt lgkmcnt(2)
	v_mfma_f32_16x16x32_bf16 v[24:27], v[24:27], v[16:19], 0
	v_cvt_pk_bf16_f32 v35, v46, v48
	v_readlane_b32 s0, v254, 34
	v_mul_u32_u24_e32 v11, 0x210, v39
	s_waitcnt lgkmcnt(1)
	v_mfma_f32_16x16x32_bf16 v[140:143], v[28:31], v[16:19], 0
	ds_read_b128 v[28:31], v8 offset:38976
	v_readlane_b32 s1, v254, 35
	s_and_b64 vcc, exec, s[0:1]
	s_waitcnt lgkmcnt(1)
	v_mfma_f32_16x16x32_bf16 v[16:19], v[136:139], v[16:19], 0
	ds_read_b128 v[136:139], v8 offset:47424
	s_waitcnt lgkmcnt(1)
	v_mfma_f32_16x16x32_bf16 v[28:31], v[28:31], v[32:35], v[20:23]
	s_nop 2
	ds_read_b128 v[20:23], v8 offset:55872
	s_waitcnt lgkmcnt(1)
	v_mfma_f32_16x16x32_bf16 v[24:27], v[136:139], v[32:35], v[24:27]
	ds_read_b128 v[136:139], v10 offset:38976
	v_mul_u32_u24_e32 v8, 0x210, v38
	v_add_u32_e32 v10, v115, v8
	s_waitcnt lgkmcnt(1)
	v_mfma_f32_16x16x32_bf16 v[20:23], v[20:23], v[32:35], v[140:143]
	v_add_u32_e32 v8, v115, v11
	s_waitcnt lgkmcnt(0)
	v_mfma_f32_16x16x32_bf16 v[16:19], v[136:139], v[32:35], v[16:19]
	s_cbranch_vccnz .LBB0_611
	v_cvt_pk_bf16_f32 v32, v47, v49
	v_cvt_pk_bf16_f32 v33, v50, v51
	v_cvt_pk_bf16_f32 v34, v62, v65
	v_cvt_pk_bf16_f32 v35, v67, v71
	ds_read_b128 v[44:47], v10 offset:39040
	ds_read_b128 v[48:51], v10 offset:47488
	s_waitcnt lgkmcnt(1)
	v_mfma_f32_16x16x32_bf16 v[28:31], v[44:47], v[32:35], v[28:31]
	s_waitcnt lgkmcnt(0)
	v_mfma_f32_16x16x32_bf16 v[24:27], v[48:51], v[32:35], v[24:27]
	ds_read_b128 v[44:47], v10 offset:55936
	ds_read_b128 v[48:51], v8 offset:39040
	s_waitcnt lgkmcnt(1)
	v_mfma_f32_16x16x32_bf16 v[20:23], v[44:47], v[32:35], v[20:23]
	v_cvt_pk_bf16_f32 v44, v70, v118
	v_cvt_pk_bf16_f32 v45, v122, v121
	v_cvt_pk_bf16_f32 v46, v120, v119
	v_cvt_pk_bf16_f32 v47, v69, v68
	s_waitcnt lgkmcnt(0)
	v_mfma_f32_16x16x32_bf16 v[16:19], v[48:51], v[32:35], v[16:19]
	ds_read_b128 v[32:35], v10 offset:47552
	ds_read_b128 v[48:51], v10 offset:56000
	ds_read_b128 v[68:71], v10 offset:39104
	s_waitcnt lgkmcnt(2)
	v_mfma_f32_16x16x32_bf16 v[24:27], v[32:35], v[44:47], v[24:27]
	ds_read_b128 v[32:35], v8 offset:39104
	s_waitcnt lgkmcnt(1)
	v_mfma_f32_16x16x32_bf16 v[28:31], v[68:71], v[44:47], v[28:31]
	v_mfma_f32_16x16x32_bf16 v[20:23], v[48:51], v[44:47], v[20:23]
	s_waitcnt lgkmcnt(0)
	v_mfma_f32_16x16x32_bf16 v[16:19], v[32:35], v[44:47], v[16:19]
	s_and_b64 vcc, exec, s[6:7]
	s_cbranch_vccz .LBB0_612
